# inproj1 gate-tile epilogue: 16 gate biases loaded once with four 16-byte loads instead of one dword load + vmcnt(0) per value
# baseline (speedup 1.0000x reference)
.LBB0_1523:
	v_mov_b32_e32 v85, v128
	s_lshl_b32 s11, s12, 1
	v_and_b32_e32 v87, 15, v85
	v_ashrrev_i32_e32 v66, 8, v85
	v_mul_u32_u24_e32 v93, 0x210, v87
	v_mul_i32_i24_e32 v89, 0x12000, v66
	v_lshlrev_b32_e32 v91, 7, v66
	v_mad_i32_i24 v66, v66, s21, v93
	v_lshlrev_b32_e32 v93, 1, v85
	v_and_b32_e32 v93, 0x180, v93
	v_and_b32_e32 v95, 48, v85
	v_add3_u32 v66, v66, v93, v95
	s_or_b32 s14, s8, s11
	s_lshl_b32 s8, s10, 8
	ds_write_b128 v66, v[60:63]
	ds_write_b128 v66, v[56:59] offset:64
	ds_write_b128 v66, v[52:55] offset:8448
	ds_write_b128 v66, v[48:51] offset:8512
	ds_write_b128 v66, v[40:43] offset:16896
	ds_write_b128 v66, v[36:39] offset:16960
	ds_write_b128 v66, v[32:35] offset:25344
	ds_write_b128 v66, v[28:31] offset:25408
	ds_write_b128 v66, v[24:27] offset:33792
	ds_write_b128 v66, v[20:23] offset:33856
	ds_write_b128 v66, v[16:19] offset:42240
	ds_write_b128 v66, v[12:15] offset:42304
	ds_write_b128 v66, v[8:11] offset:50688
	ds_write_b128 v66, v[4:7] offset:50752
	ds_write_b128 v66, v[0:3] offset:59136
	ds_write_b128 v66, v[44:47] offset:59200
	v_add_u32_e32 v0, s8, v91
	s_cmp_gt_i32 s14, 7
	s_mov_b64 s[0:1], -1
	s_waitcnt lgkmcnt(0)
	s_barrier
	s_cbranch_scc0 .LBB0_1546
	s_cmp_gt_u32 s11, 15
	s_cbranch_scc0 .LBB0_1542
	s_cmp_gt_u32 s11, 23
	s_cbranch_scc0 .LBB0_1538
	s_cmp_lg_u32 s14, 24
	s_cbranch_scc1 .LBB0_1537
	v_bfe_u32 v4, v85, 1, 7
	v_mul_u32_u24_e32 v1, 0x210, v4
	v_add3_u32 v4, v4, s8, v91
	v_lshlrev_b32_e32 v2, 6, v85
	v_ashrrev_i32_e32 v5, 31, v4
	v_and_b32_e32 v66, 64, v2
	v_lshlrev_b64 v[4:5], 7, v[4:5]
	v_or_b32_e32 v4, v4, v66
	v_add3_u32 v1, v89, v1, v66
	v_lshl_add_u64 v[2:3], s[74:75], 0, v[66:67]
	v_lshl_add_u64 v[4:5], s[86:87], 0, v[4:5]
	s_mov_b32 s8, 0
	s_mov_b64 s[10:11], 0
	global_load_dwordx4 v[200:203], v[2:3], off
	global_load_dwordx4 v[204:207], v[2:3], off offset:16
	global_load_dwordx4 v[208:211], v[2:3], off offset:32
	global_load_dwordx4 v[212:215], v[2:3], off offset:48
	s_waitcnt vmcnt(0)
	s_branch .LBB0_1529
.LBB0_1528:
	v_mov_b32_e32 v200, v204
	v_mov_b32_e32 v201, v205
	v_mov_b32_e32 v202, v206
	v_mov_b32_e32 v203, v207
	v_mov_b32_e32 v204, v208
	v_mov_b32_e32 v205, v209
	v_mov_b32_e32 v206, v210
	v_mov_b32_e32 v207, v211
	v_mov_b32_e32 v208, v212
	v_mov_b32_e32 v209, v213
	v_mov_b32_e32 v210, v214
	v_mov_b32_e32 v211, v215
	s_add_i32 s8, s8, 4
	s_add_u32 s10, s10, 16
	v_add_co_u32_e32 v8, vcc, 0x8171000, v8
	s_addc_u32 s11, s11, 0
	s_nop 0
	v_addc_co_u32_e32 v9, vcc, 0, v9, vcc
	s_cmp_lg_u32 s10, 64
	v_add_u32_e32 v1, 16, v1
	global_store_dword v[8:9], v6, off offset:12
	s_cbranch_scc0 .LBB0_1537
.LBB0_1529:
	v_lshl_add_u64 v[6:7], v[2:3], 0, s[10:11]
	v_mov_b32_e32 v8, v200
	ds_read_b32 v9, v1
	s_cmp_gt_u32 s8, 7
	s_cselect_b64 s[12:13], -1, 0
	s_cmp_lt_u32 s8, 8
	s_waitcnt lgkmcnt(0)
	v_add_f32_e32 v10, v9, v8
	s_cbranch_scc1 .LBB0_1531
	v_mul_f32_e64 v8, |v10|, s24
	v_exp_f32_e32 v22, v8
	v_max_f32_e32 v8, v10, v10
	v_min_f32_e32 v23, 0, v8
	v_add_f32_e32 v10, 1.0, v22
	v_add_f32_e32 v8, -1.0, v10
	v_sub_f32_e32 v9, v8, v10
	v_sub_f32_e32 v8, v22, v8
	v_add_f32_e32 v9, 1.0, v9
	v_add_f32_e32 v11, v8, v9
	v_frexp_mant_f32_e32 v12, v10
	v_cvt_f64_f32_e32 v[8:9], v10
	v_frexp_exp_i32_f64_e32 v8, v[8:9]
	v_cmp_gt_f32_e32 vcc, s25, v12
	s_nop 1
	v_subbrev_co_u32_e32 v16, vcc, 0, v8, vcc
	v_sub_u32_e32 v8, 0, v16
	v_ldexp_f32 v9, v10, v8
	v_add_f32_e32 v10, -1.0, v9
	v_add_f32_e32 v12, 1.0, v9
	v_ldexp_f32 v8, v11, v8
	v_add_f32_e32 v11, 1.0, v10
	v_add_f32_e32 v13, -1.0, v12
	v_sub_f32_e32 v11, v9, v11
	v_sub_f32_e32 v9, v9, v13
	v_add_f32_e32 v11, v8, v11
	v_add_f32_e32 v8, v8, v9
	v_add_f32_e32 v17, v12, v8
	v_rcp_f32_e32 v19, v17
	v_sub_f32_e32 v9, v17, v12
	v_sub_f32_e32 v18, v8, v9
	v_add_f32_e32 v9, v10, v11
	v_mul_f32_e32 v21, v9, v19
	v_sub_f32_e32 v8, v9, v10
	v_mul_f32_e32 v10, v17, v21
	v_fma_f32 v12, v21, v17, -v10
	v_fmac_f32_e32 v12, v21, v18
	v_sub_f32_e32 v20, v11, v8
	v_add_f32_e32 v8, v10, v12
	v_sub_f32_e32 v11, v9, v8
	v_pk_add_f32 v[14:15], v[8:9], v[10:11] neg_lo:[0,1] neg_hi:[0,1]
	v_mov_b32_e32 v13, v8
	v_pk_add_f32 v[8:9], v[14:15], v[12:13] neg_lo:[0,1] neg_hi:[0,1]
	v_cmp_neq_f32_e32 vcc, s27, v22
	v_add_f32_e32 v9, v20, v9
	v_add_f32_e32 v8, v8, v9
	v_add_f32_e32 v9, v11, v8
	v_mul_f32_e32 v20, v19, v9
	v_mul_f32_e32 v10, v17, v20
	v_fma_f32 v12, v20, v17, -v10
	v_fmac_f32_e32 v12, v20, v18
	v_sub_f32_e32 v11, v11, v9
	v_add_f32_e32 v17, v8, v11
	v_add_f32_e32 v8, v10, v12
	v_sub_f32_e32 v11, v9, v8
	v_pk_add_f32 v[14:15], v[8:9], v[10:11] neg_lo:[0,1] neg_hi:[0,1]
	v_mov_b32_e32 v13, v8
	v_pk_add_f32 v[8:9], v[14:15], v[12:13] neg_lo:[0,1] neg_hi:[0,1]
	s_nop 0
	v_add_f32_e32 v9, v17, v9
	v_add_f32_e32 v8, v8, v9
	v_add_f32_e32 v9, v21, v20
	v_add_f32_e32 v8, v11, v8
	v_sub_f32_e32 v10, v9, v21
	v_mul_f32_e32 v8, v19, v8
	v_sub_f32_e32 v10, v20, v10
	v_add_f32_e32 v10, v10, v8
	v_add_f32_e32 v12, v9, v10
	v_mul_f32_e32 v13, v12, v12
	v_fmamk_f32 v8, v13, 0x3e9b6dac, v75
	v_fmaak_f32 v95, v13, v8, 0x3f2aaada
	v_cvt_f32_i32_e32 v8, v16
	v_sub_f32_e32 v9, v12, v9
	v_sub_f32_e32 v9, v10, v9
	v_ldexp_f32 v14, v9, 1
	v_mul_f32_e32 v9, v12, v13
	v_ldexp_f32 v11, v12, 1
	v_pk_mul_f32 v[12:13], v[8:9], v[94:95]
	s_nop 0
	v_fma_f32 v10, v8, s26, -v12
	v_fmac_f32_e32 v10, 0xb102e308, v8
	v_pk_add_f32 v[8:9], v[12:13], v[10:11]
	s_nop 0
	v_sub_f32_e32 v11, v9, v11
	v_sub_f32_e32 v11, v13, v11
	v_add_f32_e32 v15, v14, v11
	v_mov_b32_e32 v14, v12
	v_pk_add_f32 v[12:13], v[8:9], v[12:13] neg_lo:[0,1] neg_hi:[0,1]
	v_pk_add_f32 v[16:17], v[8:9], v[14:15]
	v_mov_b32_e32 v11, v8
	v_mov_b32_e32 v13, v17
	v_pk_add_f32 v[18:19], v[10:11], v[12:13] neg_lo:[0,1] neg_hi:[0,1]
	v_pk_add_f32 v[10:11], v[10:11], v[12:13]
	v_mov_b32_e32 v14, v15
	v_pk_add_f32 v[12:13], v[10:11], v[8:9] op_sel:[1,0] op_sel_hi:[0,1] neg_lo:[0,1] neg_hi:[0,1]
	v_pk_add_f32 v[20:21], v[16:17], v[12:13] op_sel_hi:[1,0] neg_lo:[0,1] neg_hi:[0,1]
	v_mov_b32_e32 v16, v17
	v_mov_b32_e32 v17, v11
	v_pk_mov_b32 v[12:13], v[8:9], v[12:13] op_sel:[1,0]
	v_mov_b32_e32 v15, v8
	v_pk_add_f32 v[12:13], v[16:17], v[12:13] neg_lo:[0,1] neg_hi:[0,1]
	v_mov_b32_e32 v20, v18
	v_pk_add_f32 v[8:9], v[14:15], v[12:13] neg_lo:[0,1] neg_hi:[0,1]
	v_mov_b32_e32 v19, v11
	v_pk_add_f32 v[12:13], v[20:21], v[8:9]
	s_nop 0
	v_pk_add_f32 v[14:15], v[12:13], v[12:13] op_sel:[0,1] op_sel_hi:[1,0]
	s_nop 0
	v_pk_add_f32 v[10:11], v[10:11], v[14:15] op_sel:[1,0] op_sel_hi:[0,1]
	v_mov_b32_e32 v13, v10
	v_pk_add_f32 v[16:17], v[12:13], v[18:19] neg_lo:[0,1] neg_hi:[0,1]
	v_mov_b32_e32 v9, v14
	v_sub_f32_e32 v11, v12, v16
	v_pk_add_f32 v[8:9], v[8:9], v[16:17] neg_lo:[0,1] neg_hi:[0,1]
	v_sub_f32_e32 v11, v18, v11
	v_add_f32_e32 v8, v8, v11
	v_add_f32_e32 v8, v8, v9
	v_add_f32_e32 v8, v10, v8
	v_cndmask_b32_e32 v8, v77, v8, vcc
	v_cmp_ngt_f32_e32 vcc, -1.0, v22
	s_nop 1
	v_cndmask_b32_e32 v8, v79, v8, vcc
	v_cmp_neq_f32_e32 vcc, -1.0, v22
	s_nop 1
	v_cndmask_b32_e32 v8, v81, v8, vcc
	v_cmp_lt_f32_e64 vcc, |v22|, s28
	s_nop 1
	v_cndmask_b32_e32 v8, v8, v22, vcc
	v_sub_f32_e32 v10, v23, v8
.LBB0_1531:
	v_lshl_add_u64 v[8:9], v[4:5], 0, s[10:11]
	v_add_co_u32_e32 v12, vcc, 0x8171000, v8
	ds_read_b32 v11, v1 offset:4
	s_nop 0
	v_addc_co_u32_e32 v13, vcc, 0, v9, vcc
	global_store_dword v[12:13], v10, off
	v_mov_b32_e32 v10, v201
	v_cndmask_b32_e64 v12, 0, 1, s[12:13]
	v_cmp_ne_u32_e64 s[0:1], 1, v12
	s_andn2_b64 vcc, exec, s[12:13]
	s_waitcnt lgkmcnt(0)
	v_add_f32_e32 v10, v11, v10
	s_cbranch_vccnz .LBB0_1533
	v_mul_f32_e64 v11, |v10|, s24
	v_exp_f32_e32 v24, v11
	v_max_f32_e32 v10, v10, v10
	v_min_f32_e32 v25, 0, v10
	v_add_f32_e32 v12, 1.0, v24
	v_add_f32_e32 v10, -1.0, v12
	v_sub_f32_e32 v11, v10, v12
	v_sub_f32_e32 v10, v24, v10
	v_add_f32_e32 v11, 1.0, v11
	v_add_f32_e32 v13, v10, v11
	v_frexp_mant_f32_e32 v14, v12
	v_cvt_f64_f32_e32 v[10:11], v12
	v_frexp_exp_i32_f64_e32 v10, v[10:11]
	v_cmp_gt_f32_e32 vcc, s25, v14
	s_nop 1
	v_subbrev_co_u32_e32 v18, vcc, 0, v10, vcc
	v_sub_u32_e32 v10, 0, v18
	v_ldexp_f32 v11, v12, v10
	v_add_f32_e32 v12, -1.0, v11
	v_add_f32_e32 v14, 1.0, v11
	v_ldexp_f32 v10, v13, v10
	v_add_f32_e32 v13, 1.0, v12
	v_add_f32_e32 v15, -1.0, v14
	v_sub_f32_e32 v13, v11, v13
	v_sub_f32_e32 v11, v11, v15
	v_add_f32_e32 v13, v10, v13
	v_add_f32_e32 v10, v10, v11
	v_add_f32_e32 v19, v14, v10
	v_rcp_f32_e32 v21, v19
	v_sub_f32_e32 v11, v19, v14
	v_sub_f32_e32 v20, v10, v11
	v_add_f32_e32 v11, v12, v13
	v_mul_f32_e32 v23, v11, v21
	v_sub_f32_e32 v10, v11, v12
	v_mul_f32_e32 v12, v19, v23
	v_fma_f32 v14, v23, v19, -v12
	v_fmac_f32_e32 v14, v23, v20
	v_sub_f32_e32 v22, v13, v10
	v_add_f32_e32 v10, v12, v14
	v_sub_f32_e32 v13, v11, v10
	v_pk_add_f32 v[16:17], v[10:11], v[12:13] neg_lo:[0,1] neg_hi:[0,1]
	v_mov_b32_e32 v15, v10
	v_pk_add_f32 v[10:11], v[16:17], v[14:15] neg_lo:[0,1] neg_hi:[0,1]
	v_cmp_neq_f32_e32 vcc, s27, v24
	v_add_f32_e32 v11, v22, v11
	v_add_f32_e32 v10, v10, v11
	v_add_f32_e32 v11, v13, v10
	v_mul_f32_e32 v22, v21, v11
	v_mul_f32_e32 v12, v19, v22
	v_fma_f32 v14, v22, v19, -v12
	v_fmac_f32_e32 v14, v22, v20
	v_sub_f32_e32 v13, v13, v11
	v_add_f32_e32 v19, v10, v13
	v_add_f32_e32 v10, v12, v14
	v_sub_f32_e32 v13, v11, v10
	v_pk_add_f32 v[16:17], v[10:11], v[12:13] neg_lo:[0,1] neg_hi:[0,1]
	v_mov_b32_e32 v15, v10
	v_pk_add_f32 v[10:11], v[16:17], v[14:15] neg_lo:[0,1] neg_hi:[0,1]
	s_nop 0
	v_add_f32_e32 v11, v19, v11
	v_add_f32_e32 v10, v10, v11
	v_add_f32_e32 v11, v23, v22
	v_add_f32_e32 v10, v13, v10
	v_sub_f32_e32 v12, v11, v23
	v_mul_f32_e32 v10, v21, v10
	v_sub_f32_e32 v12, v22, v12
	v_add_f32_e32 v12, v12, v10
	v_add_f32_e32 v14, v11, v12
	v_mul_f32_e32 v15, v14, v14
	v_fmamk_f32 v10, v15, 0x3e9b6dac, v75
	v_fmaak_f32 v95, v15, v10, 0x3f2aaada
	v_cvt_f32_i32_e32 v10, v18
	v_sub_f32_e32 v11, v14, v11
	v_sub_f32_e32 v11, v12, v11
	v_ldexp_f32 v16, v11, 1
	v_mul_f32_e32 v11, v14, v15
	v_ldexp_f32 v13, v14, 1
	v_pk_mul_f32 v[14:15], v[10:11], v[94:95]
	s_nop 0
	v_fma_f32 v12, v10, s26, -v14
	v_fmac_f32_e32 v12, 0xb102e308, v10
	v_pk_add_f32 v[10:11], v[14:15], v[12:13]
	s_nop 0
	v_sub_f32_e32 v13, v11, v13
	v_sub_f32_e32 v13, v15, v13
	v_add_f32_e32 v17, v16, v13
	v_mov_b32_e32 v16, v14
	v_pk_add_f32 v[14:15], v[10:11], v[14:15] neg_lo:[0,1] neg_hi:[0,1]
	v_pk_add_f32 v[18:19], v[10:11], v[16:17]
	v_mov_b32_e32 v13, v10
	v_mov_b32_e32 v15, v19
	v_pk_add_f32 v[20:21], v[12:13], v[14:15] neg_lo:[0,1] neg_hi:[0,1]
	v_pk_add_f32 v[12:13], v[12:13], v[14:15]
	v_mov_b32_e32 v16, v17
	v_pk_add_f32 v[14:15], v[12:13], v[10:11] op_sel:[1,0] op_sel_hi:[0,1] neg_lo:[0,1] neg_hi:[0,1]
	v_pk_add_f32 v[22:23], v[18:19], v[14:15] op_sel_hi:[1,0] neg_lo:[0,1] neg_hi:[0,1]
	v_mov_b32_e32 v18, v19
	v_mov_b32_e32 v19, v13
	v_pk_mov_b32 v[14:15], v[10:11], v[14:15] op_sel:[1,0]
	v_mov_b32_e32 v17, v10
	v_pk_add_f32 v[14:15], v[18:19], v[14:15] neg_lo:[0,1] neg_hi:[0,1]
	v_mov_b32_e32 v22, v20
	v_pk_add_f32 v[10:11], v[16:17], v[14:15] neg_lo:[0,1] neg_hi:[0,1]
	v_mov_b32_e32 v21, v13
	v_pk_add_f32 v[14:15], v[22:23], v[10:11]
	s_nop 0
	v_pk_add_f32 v[16:17], v[14:15], v[14:15] op_sel:[0,1] op_sel_hi:[1,0]
	s_nop 0
	v_pk_add_f32 v[12:13], v[12:13], v[16:17] op_sel:[1,0] op_sel_hi:[0,1]
	v_mov_b32_e32 v15, v12
	v_pk_add_f32 v[18:19], v[14:15], v[20:21] neg_lo:[0,1] neg_hi:[0,1]
	v_mov_b32_e32 v11, v16
	v_sub_f32_e32 v13, v14, v18
	v_pk_add_f32 v[10:11], v[10:11], v[18:19] neg_lo:[0,1] neg_hi:[0,1]
	v_sub_f32_e32 v13, v20, v13
	v_add_f32_e32 v10, v10, v13
	v_add_f32_e32 v10, v10, v11
	v_add_f32_e32 v10, v12, v10
	v_cndmask_b32_e32 v10, v77, v10, vcc
	v_cmp_ngt_f32_e32 vcc, -1.0, v24
	s_nop 1
	v_cndmask_b32_e32 v10, v79, v10, vcc
	v_cmp_neq_f32_e32 vcc, -1.0, v24
	s_nop 1
	v_cndmask_b32_e32 v10, v81, v10, vcc
	v_cmp_lt_f32_e64 vcc, |v24|, s28
	s_nop 1
	v_cndmask_b32_e32 v10, v10, v24, vcc
	v_sub_f32_e32 v10, v25, v10
.LBB0_1533:
	v_add_co_u32_e32 v12, vcc, 0x8171000, v8
	ds_read_b32 v11, v1 offset:8
	s_nop 0
	v_addc_co_u32_e32 v13, vcc, 0, v9, vcc
	global_store_dword v[12:13], v10, off offset:4
	v_mov_b32_e32 v10, v202
	s_and_b64 vcc, exec, s[0:1]
	s_waitcnt lgkmcnt(0)
	v_add_f32_e32 v10, v11, v10
	s_cbranch_vccnz .LBB0_1535
	v_mul_f32_e64 v11, |v10|, s24
	v_exp_f32_e32 v24, v11
	v_max_f32_e32 v10, v10, v10
	v_min_f32_e32 v25, 0, v10
	v_add_f32_e32 v12, 1.0, v24
	v_add_f32_e32 v10, -1.0, v12
	v_sub_f32_e32 v11, v10, v12
	v_sub_f32_e32 v10, v24, v10
	v_add_f32_e32 v11, 1.0, v11
	v_add_f32_e32 v13, v10, v11
	v_frexp_mant_f32_e32 v14, v12
	v_cvt_f64_f32_e32 v[10:11], v12
	v_frexp_exp_i32_f64_e32 v10, v[10:11]
	v_cmp_gt_f32_e32 vcc, s25, v14
	s_nop 1
	v_subbrev_co_u32_e32 v18, vcc, 0, v10, vcc
	v_sub_u32_e32 v10, 0, v18
	v_ldexp_f32 v11, v12, v10
	v_add_f32_e32 v12, -1.0, v11
	v_add_f32_e32 v14, 1.0, v11
	v_ldexp_f32 v10, v13, v10
	v_add_f32_e32 v13, 1.0, v12
	v_add_f32_e32 v15, -1.0, v14
	v_sub_f32_e32 v13, v11, v13
	v_sub_f32_e32 v11, v11, v15
	v_add_f32_e32 v13, v10, v13
	v_add_f32_e32 v10, v10, v11
	v_add_f32_e32 v19, v14, v10
	v_rcp_f32_e32 v21, v19
	v_sub_f32_e32 v11, v19, v14
	v_sub_f32_e32 v20, v10, v11
	v_add_f32_e32 v11, v12, v13
	v_mul_f32_e32 v23, v11, v21
	v_sub_f32_e32 v10, v11, v12
	v_mul_f32_e32 v12, v19, v23
	v_fma_f32 v14, v23, v19, -v12
	v_fmac_f32_e32 v14, v23, v20
	v_sub_f32_e32 v22, v13, v10
	v_add_f32_e32 v10, v12, v14
	v_sub_f32_e32 v13, v11, v10
	v_pk_add_f32 v[16:17], v[10:11], v[12:13] neg_lo:[0,1] neg_hi:[0,1]
	v_mov_b32_e32 v15, v10
	v_pk_add_f32 v[10:11], v[16:17], v[14:15] neg_lo:[0,1] neg_hi:[0,1]
	v_cmp_neq_f32_e32 vcc, s27, v24
	v_add_f32_e32 v11, v22, v11
	v_add_f32_e32 v10, v10, v11
	v_add_f32_e32 v11, v13, v10
	v_mul_f32_e32 v22, v21, v11
	v_mul_f32_e32 v12, v19, v22
	v_fma_f32 v14, v22, v19, -v12
	v_fmac_f32_e32 v14, v22, v20
	v_sub_f32_e32 v13, v13, v11
	v_add_f32_e32 v19, v10, v13
	v_add_f32_e32 v10, v12, v14
	v_sub_f32_e32 v13, v11, v10
	v_pk_add_f32 v[16:17], v[10:11], v[12:13] neg_lo:[0,1] neg_hi:[0,1]
	v_mov_b32_e32 v15, v10
	v_pk_add_f32 v[10:11], v[16:17], v[14:15] neg_lo:[0,1] neg_hi:[0,1]
	s_nop 0
	v_add_f32_e32 v11, v19, v11
	v_add_f32_e32 v10, v10, v11
	v_add_f32_e32 v11, v23, v22
	v_add_f32_e32 v10, v13, v10
	v_sub_f32_e32 v12, v11, v23
	v_mul_f32_e32 v10, v21, v10
	v_sub_f32_e32 v12, v22, v12
	v_add_f32_e32 v12, v12, v10
	v_add_f32_e32 v14, v11, v12
	v_mul_f32_e32 v15, v14, v14
	v_fmamk_f32 v10, v15, 0x3e9b6dac, v75
	v_fmaak_f32 v95, v15, v10, 0x3f2aaada
	v_cvt_f32_i32_e32 v10, v18
	v_sub_f32_e32 v11, v14, v11
	v_sub_f32_e32 v11, v12, v11
	v_ldexp_f32 v16, v11, 1
	v_mul_f32_e32 v11, v14, v15
	v_ldexp_f32 v13, v14, 1
	v_pk_mul_f32 v[14:15], v[10:11], v[94:95]
	s_nop 0
	v_fma_f32 v12, v10, s26, -v14
	v_fmac_f32_e32 v12, 0xb102e308, v10
	v_pk_add_f32 v[10:11], v[14:15], v[12:13]
	s_nop 0
	v_sub_f32_e32 v13, v11, v13
	v_sub_f32_e32 v13, v15, v13
	v_add_f32_e32 v17, v16, v13
	v_mov_b32_e32 v16, v14
	v_pk_add_f32 v[14:15], v[10:11], v[14:15] neg_lo:[0,1] neg_hi:[0,1]
	v_pk_add_f32 v[18:19], v[10:11], v[16:17]
	v_mov_b32_e32 v13, v10
	v_mov_b32_e32 v15, v19
	v_pk_add_f32 v[20:21], v[12:13], v[14:15] neg_lo:[0,1] neg_hi:[0,1]
	v_pk_add_f32 v[12:13], v[12:13], v[14:15]
	v_mov_b32_e32 v16, v17
	v_pk_add_f32 v[14:15], v[12:13], v[10:11] op_sel:[1,0] op_sel_hi:[0,1] neg_lo:[0,1] neg_hi:[0,1]
	v_pk_add_f32 v[22:23], v[18:19], v[14:15] op_sel_hi:[1,0] neg_lo:[0,1] neg_hi:[0,1]
	v_mov_b32_e32 v18, v19
	v_mov_b32_e32 v19, v13
	v_pk_mov_b32 v[14:15], v[10:11], v[14:15] op_sel:[1,0]
	v_mov_b32_e32 v17, v10
	v_pk_add_f32 v[14:15], v[18:19], v[14:15] neg_lo:[0,1] neg_hi:[0,1]
	v_mov_b32_e32 v22, v20
	v_pk_add_f32 v[10:11], v[16:17], v[14:15] neg_lo:[0,1] neg_hi:[0,1]
	v_mov_b32_e32 v21, v13
	v_pk_add_f32 v[14:15], v[22:23], v[10:11]
	s_nop 0
	v_pk_add_f32 v[16:17], v[14:15], v[14:15] op_sel:[0,1] op_sel_hi:[1,0]
	s_nop 0
	v_pk_add_f32 v[12:13], v[12:13], v[16:17] op_sel:[1,0] op_sel_hi:[0,1]
	v_mov_b32_e32 v15, v12
	v_pk_add_f32 v[18:19], v[14:15], v[20:21] neg_lo:[0,1] neg_hi:[0,1]
	v_mov_b32_e32 v11, v16
	v_sub_f32_e32 v13, v14, v18
	v_pk_add_f32 v[10:11], v[10:11], v[18:19] neg_lo:[0,1] neg_hi:[0,1]
	v_sub_f32_e32 v13, v20, v13
	v_add_f32_e32 v10, v10, v13
	v_add_f32_e32 v10, v10, v11
	v_add_f32_e32 v10, v12, v10
	v_cndmask_b32_e32 v10, v77, v10, vcc
	v_cmp_ngt_f32_e32 vcc, -1.0, v24
	s_nop 1
	v_cndmask_b32_e32 v10, v79, v10, vcc
	v_cmp_neq_f32_e32 vcc, -1.0, v24
	s_nop 1
	v_cndmask_b32_e32 v10, v81, v10, vcc
	v_cmp_lt_f32_e64 vcc, |v24|, s28
	s_nop 1
	v_cndmask_b32_e32 v10, v10, v24, vcc
	v_sub_f32_e32 v10, v25, v10
.LBB0_1535:
	v_add_co_u32_e32 v12, vcc, 0x8171000, v8
	s_nop 1
	v_addc_co_u32_e32 v13, vcc, 0, v9, vcc
	global_store_dword v[12:13], v10, off offset:8
	v_mov_b32_e32 v6, v203
	ds_read_b32 v7, v1 offset:12
	s_and_b64 vcc, exec, s[0:1]
	s_waitcnt lgkmcnt(0)
	v_add_f32_e32 v6, v7, v6
	s_cbranch_vccnz .LBB0_1528
	v_mul_f32_e64 v7, |v6|, s24
	v_exp_f32_e32 v22, v7
	v_max_f32_e32 v6, v6, v6
	v_min_f32_e32 v23, 0, v6
	v_add_f32_e32 v10, 1.0, v22
	v_add_f32_e32 v6, -1.0, v10
	v_sub_f32_e32 v7, v6, v10
	v_sub_f32_e32 v6, v22, v6
	v_add_f32_e32 v7, 1.0, v7
	v_add_f32_e32 v11, v6, v7
	v_frexp_mant_f32_e32 v12, v10
	v_cvt_f64_f32_e32 v[6:7], v10
	v_frexp_exp_i32_f64_e32 v6, v[6:7]
	v_cmp_gt_f32_e32 vcc, s25, v12
	s_nop 1
	v_subbrev_co_u32_e32 v16, vcc, 0, v6, vcc
	v_sub_u32_e32 v6, 0, v16
	v_ldexp_f32 v7, v10, v6
	v_add_f32_e32 v10, -1.0, v7
	v_add_f32_e32 v12, 1.0, v7
	v_ldexp_f32 v6, v11, v6
	v_add_f32_e32 v11, 1.0, v10
	v_add_f32_e32 v13, -1.0, v12
	v_sub_f32_e32 v11, v7, v11
	v_sub_f32_e32 v7, v7, v13
	v_add_f32_e32 v11, v6, v11
	v_add_f32_e32 v6, v6, v7
	v_add_f32_e32 v17, v12, v6
	v_rcp_f32_e32 v19, v17
	v_sub_f32_e32 v7, v17, v12
	v_sub_f32_e32 v18, v6, v7
	v_add_f32_e32 v7, v10, v11
	v_mul_f32_e32 v21, v7, v19
	v_sub_f32_e32 v6, v7, v10
	v_mul_f32_e32 v10, v17, v21
	v_fma_f32 v12, v21, v17, -v10
	v_fmac_f32_e32 v12, v21, v18
	v_sub_f32_e32 v20, v11, v6
	v_add_f32_e32 v6, v10, v12
	v_sub_f32_e32 v11, v7, v6
	v_pk_add_f32 v[14:15], v[6:7], v[10:11] neg_lo:[0,1] neg_hi:[0,1]
	v_mov_b32_e32 v13, v6
	v_pk_add_f32 v[6:7], v[14:15], v[12:13] neg_lo:[0,1] neg_hi:[0,1]
	v_cmp_neq_f32_e32 vcc, s27, v22
	v_add_f32_e32 v7, v20, v7
	v_add_f32_e32 v6, v6, v7
	v_add_f32_e32 v7, v11, v6
	v_mul_f32_e32 v20, v19, v7
	v_mul_f32_e32 v10, v17, v20
	v_fma_f32 v12, v20, v17, -v10
	v_fmac_f32_e32 v12, v20, v18
	v_sub_f32_e32 v11, v11, v7
	v_add_f32_e32 v17, v6, v11
	v_add_f32_e32 v6, v10, v12
	v_sub_f32_e32 v11, v7, v6
	v_pk_add_f32 v[14:15], v[6:7], v[10:11] neg_lo:[0,1] neg_hi:[0,1]
	v_mov_b32_e32 v13, v6
	v_pk_add_f32 v[6:7], v[14:15], v[12:13] neg_lo:[0,1] neg_hi:[0,1]
	s_nop 0
	v_add_f32_e32 v7, v17, v7
	v_add_f32_e32 v6, v6, v7
	v_add_f32_e32 v7, v21, v20
	v_add_f32_e32 v6, v11, v6
	v_sub_f32_e32 v10, v7, v21
	v_mul_f32_e32 v6, v19, v6
	v_sub_f32_e32 v10, v20, v10
	v_add_f32_e32 v10, v10, v6
	v_add_f32_e32 v12, v7, v10
	v_mul_f32_e32 v13, v12, v12
	v_fmamk_f32 v6, v13, 0x3e9b6dac, v75
	v_fmaak_f32 v95, v13, v6, 0x3f2aaada
	v_cvt_f32_i32_e32 v6, v16
	v_sub_f32_e32 v7, v12, v7
	v_sub_f32_e32 v7, v10, v7
	v_ldexp_f32 v14, v7, 1
	v_mul_f32_e32 v7, v12, v13
	v_ldexp_f32 v11, v12, 1
	v_pk_mul_f32 v[12:13], v[6:7], v[94:95]
	s_nop 0
	v_fma_f32 v10, v6, s26, -v12
	v_fmac_f32_e32 v10, 0xb102e308, v6
	v_pk_add_f32 v[6:7], v[12:13], v[10:11]
	s_nop 0
	v_sub_f32_e32 v11, v7, v11
	v_sub_f32_e32 v11, v13, v11
	v_add_f32_e32 v15, v14, v11
	v_mov_b32_e32 v14, v12
	v_pk_add_f32 v[12:13], v[6:7], v[12:13] neg_lo:[0,1] neg_hi:[0,1]
	v_pk_add_f32 v[16:17], v[6:7], v[14:15]
	v_mov_b32_e32 v11, v6
	v_mov_b32_e32 v13, v17
	v_pk_add_f32 v[18:19], v[10:11], v[12:13] neg_lo:[0,1] neg_hi:[0,1]
	v_pk_add_f32 v[10:11], v[10:11], v[12:13]
	v_mov_b32_e32 v14, v15
	v_pk_add_f32 v[12:13], v[10:11], v[6:7] op_sel:[1,0] op_sel_hi:[0,1] neg_lo:[0,1] neg_hi:[0,1]
	v_pk_add_f32 v[20:21], v[16:17], v[12:13] op_sel_hi:[1,0] neg_lo:[0,1] neg_hi:[0,1]
	v_mov_b32_e32 v16, v17
	v_mov_b32_e32 v17, v11
	v_pk_mov_b32 v[12:13], v[6:7], v[12:13] op_sel:[1,0]
	v_mov_b32_e32 v15, v6
	v_pk_add_f32 v[12:13], v[16:17], v[12:13] neg_lo:[0,1] neg_hi:[0,1]
	v_mov_b32_e32 v20, v18
	v_pk_add_f32 v[6:7], v[14:15], v[12:13] neg_lo:[0,1] neg_hi:[0,1]
	v_mov_b32_e32 v19, v11
	v_pk_add_f32 v[12:13], v[20:21], v[6:7]
	s_nop 0
	v_pk_add_f32 v[14:15], v[12:13], v[12:13] op_sel:[0,1] op_sel_hi:[1,0]
	s_nop 0
	v_pk_add_f32 v[10:11], v[10:11], v[14:15] op_sel:[1,0] op_sel_hi:[0,1]
	v_mov_b32_e32 v13, v10
	v_pk_add_f32 v[16:17], v[12:13], v[18:19] neg_lo:[0,1] neg_hi:[0,1]
	v_mov_b32_e32 v7, v14
	v_sub_f32_e32 v11, v12, v16
	v_pk_add_f32 v[6:7], v[6:7], v[16:17] neg_lo:[0,1] neg_hi:[0,1]
	v_sub_f32_e32 v11, v18, v11
	v_add_f32_e32 v6, v6, v11
	v_add_f32_e32 v6, v6, v7
	v_add_f32_e32 v6, v10, v6
	v_cndmask_b32_e32 v6, v77, v6, vcc
	v_cmp_ngt_f32_e32 vcc, -1.0, v22
	s_nop 1
	v_cndmask_b32_e32 v6, v79, v6, vcc
	v_cmp_neq_f32_e32 vcc, -1.0, v22
	s_nop 1
	v_cndmask_b32_e32 v6, v81, v6, vcc
	v_cmp_lt_f32_e64 vcc, |v22|, s28
	s_nop 1
	v_cndmask_b32_e32 v6, v6, v22, vcc
	v_sub_f32_e32 v6, v23, v6
	s_branch .LBB0_1528
